# in-projection epilogue: the eight RMSNorm row-sum loads issued together, one wait (on top of hand-written diff-attention epilogue)
# baseline (speedup 1.0000x reference)
; __device__ __forceinline__ unsigned cvt_pk_bf16(float lo, float hi) { unsigned r; asm volatile("v_cvt_pk_bf16_f32 %0, %1, %2" : "=v"(r) : "v"(lo), "v"(hi)); return r; }
;     __device__ __forceinline__ void operator()(const f32x4 (&acc)[2][2][4][2], const Unit& u, int wr, int wc, int fr, int fq) const {
;     ...
;         const int row0 = u.pm * BM + wr * 64 + fr; const int col0 = u.pn * BM + wc * 32 + 8 * fq;
; #pragma unroll
;         for (int ai = 0; ai < 2; ++ai)
; #pragma unroll
;             for (int m = 0; m < 4; ++m) { const int row = row0 + ai * HALF + m * 16; bf16_t* rowp = O + (size_t)row * ldc + col0;
;                 const float rs = ssq ? __builtin_amdgcn_rsqf(ssq[row] * (1.f / 2048.f) + 1e-6f) : 1.f;
; #pragma unroll
;                 for (int bj = 0; bj < 2; ++bj) { f32x4 v0 = acc[ai][bj][m][0] * rs, v1 = acc[ai][bj][m][1] * rs;
;                     if (ACT == 1) {
; #pragma unroll
;                         for (int e = 0; e < 4; ++e) { float a = fmaxf(v0[e], 0.f), b = fmaxf(v1[e], 0.f); v0[e] = a * a; v1[e] = b * b; } }
;                     u32x4 w; w.x = cvt_pk_bf16(v0[0], v0[1]); w.y = cvt_pk_bf16(v0[2], v0[3]); w.z = cvt_pk_bf16(v1[0], v1[1]); w.w = cvt_pk_bf16(v1[2], v1[3]);
;                     if (ACT == 1) __builtin_nontemporal_store(w, (u32x4*)(rowp + bj * HALF)); else *(u32x4*)(rowp + bj * HALF) = w; } }
.LBB0_69:
	v_mov_b32_e32 v138, v145
	v_mov_b32_e32 v142, v147
	s_lshl_b32 s4, s89, 8
	s_add_i32 s4, s4, s64
	v_add_u32_e32 v138, s4, v138
	v_ashrrev_i32_e32 v139, 31, v138
	v_cndmask_b32_e64 v140, 0, 1, s[46:47]
	v_mov_b32_e32 v144, 1.0
	v_cmp_ne_u32_e64 s[4:5], 1, v140
	s_andn2_b64 vcc, exec, s[46:47]
	v_lshl_add_u64 v[140:141], v[138:139], 2, s[10:11]
	v_mov_b32_e32 v146, 1.0
	s_cbranch_vccnz .LBB0_71
	global_load_dword v220, v[140:141], off
	global_load_dword v221, v[140:141], off offset:64
	global_load_dword v222, v[140:141], off offset:128
	global_load_dword v223, v[140:141], off offset:192
	global_load_dword v224, v[140:141], off offset:512
	global_load_dword v225, v[140:141], off offset:576
	global_load_dword v226, v[140:141], off offset:640
	global_load_dword v227, v[140:141], off offset:704
	s_waitcnt vmcnt(0)
	v_fmamk_f32 v139, v220, 0x3a000000, v239
	v_rsq_f32_e32 v146, v139
.LBB0_71:
	s_lshl_b32 s34, s88, 8
	s_or_b32 s34, s34, s84
	v_lshl_add_u32 v142, v142, 3, s34
	v_mov_b64_e32 v[150:151], s[20:21]
	v_ashrrev_i32_e32 v143, 31, v142
	v_mad_i64_i32 v[150:151], s[62:63], v138, s53, v[150:151]
	v_lshl_add_u64 v[150:151], v[142:143], 1, v[150:151]
	v_pk_mul_f32 v[126:127], v[126:127], v[146:147] op_sel_hi:[1,0]
	v_pk_mul_f32 v[124:125], v[124:125], v[146:147] op_sel_hi:[1,0]
	v_pk_mul_f32 v[152:153], v[122:123], v[146:147] op_sel_hi:[1,0]
	v_pk_mul_f32 v[122:123], v[120:121], v[146:147] op_sel_hi:[1,0]
	v_cvt_pk_bf16_f32 v120, v124, v125
	v_cvt_pk_bf16_f32 v121, v126, v127
	s_and_b64 vcc, exec, s[4:5]
	v_cvt_pk_bf16_f32 v122, v122, v123
	v_cvt_pk_bf16_f32 v123, v152, v153
	global_store_dwordx4 v[150:151], v[120:123], off
	v_pk_mul_f32 v[118:119], v[118:119], v[146:147] op_sel_hi:[1,0]
	v_pk_mul_f32 v[116:117], v[116:117], v[146:147] op_sel_hi:[1,0]
	v_pk_mul_f32 v[120:121], v[114:115], v[146:147] op_sel_hi:[1,0]
	v_pk_mul_f32 v[114:115], v[112:113], v[146:147] op_sel_hi:[1,0]
	v_cvt_pk_bf16_f32 v112, v116, v117
	v_cvt_pk_bf16_f32 v113, v118, v119
	s_nop 0
	v_cvt_pk_bf16_f32 v114, v114, v115
	v_cvt_pk_bf16_f32 v115, v120, v121
	global_store_dwordx4 v[150:151], v[112:115], off offset:256
	s_cbranch_vccnz .LBB0_73
	s_nop 1
	v_fmamk_f32 v112, v221, 0x3a000000, v239
	v_rsq_f32_e32 v144, v112
.LBB0_73:
	s_nop 0
	v_add_u32_e32 v114, 16, v138
	v_mov_b64_e32 v[112:113], s[20:21]
	v_mad_i64_i32 v[112:113], s[62:63], v114, s53, v[112:113]
	v_lshl_add_u64 v[112:113], v[142:143], 1, v[112:113]
	v_pk_mul_f32 v[110:111], v[110:111], v[144:145] op_sel_hi:[1,0]
	v_pk_mul_f32 v[108:109], v[108:109], v[144:145] op_sel_hi:[1,0]
	v_pk_mul_f32 v[114:115], v[106:107], v[144:145] op_sel_hi:[1,0]
	v_pk_mul_f32 v[106:107], v[104:105], v[144:145] op_sel_hi:[1,0]
	v_cvt_pk_bf16_f32 v104, v108, v109
	v_cvt_pk_bf16_f32 v105, v110, v111
	v_pk_mul_f32 v[102:103], v[102:103], v[144:145] op_sel_hi:[1,0]
	v_cvt_pk_bf16_f32 v106, v106, v107
	v_cvt_pk_bf16_f32 v107, v114, v115
	global_store_dwordx4 v[112:113], v[104:107], off
	v_pk_mul_f32 v[100:101], v[100:101], v[144:145] op_sel_hi:[1,0]
	s_and_b64 vcc, exec, s[4:5]
	v_pk_mul_f32 v[104:105], v[98:99], v[144:145] op_sel_hi:[1,0]
	v_pk_mul_f32 v[98:99], v[96:97], v[144:145] op_sel_hi:[1,0]
	v_cvt_pk_bf16_f32 v96, v100, v101
	v_cvt_pk_bf16_f32 v97, v102, v103
	s_nop 0
	v_cvt_pk_bf16_f32 v98, v98, v99
	v_cvt_pk_bf16_f32 v99, v104, v105
	global_store_dwordx4 v[112:113], v[96:99], off offset:256
	s_nop 1
	v_mov_b32_e32 v96, 1.0
	v_mov_b32_e32 v98, 1.0
	s_cbranch_vccnz .LBB0_75
	s_nop 1
	v_fmamk_f32 v97, v222, 0x3a000000, v239
	v_rsq_f32_e32 v98, v97
.LBB0_75:
	v_add_u32_e32 v97, 32, v138
	v_mov_b64_e32 v[100:101], s[20:21]
	v_mad_i64_i32 v[100:101], s[62:63], v97, s53, v[100:101]
	v_lshl_add_u64 v[100:101], v[142:143], 1, v[100:101]
	v_pk_mul_f32 v[94:95], v[94:95], v[98:99] op_sel_hi:[1,0]
	v_pk_mul_f32 v[92:93], v[92:93], v[98:99] op_sel_hi:[1,0]
	v_pk_mul_f32 v[102:103], v[90:91], v[98:99] op_sel_hi:[1,0]
	v_pk_mul_f32 v[90:91], v[88:89], v[98:99] op_sel_hi:[1,0]
	v_cvt_pk_bf16_f32 v88, v92, v93
	v_cvt_pk_bf16_f32 v89, v94, v95
	s_and_b64 vcc, exec, s[4:5]
	v_cvt_pk_bf16_f32 v90, v90, v91
	v_cvt_pk_bf16_f32 v91, v102, v103
	global_store_dwordx4 v[100:101], v[88:91], off
	v_pk_mul_f32 v[86:87], v[86:87], v[98:99] op_sel_hi:[1,0]
	v_pk_mul_f32 v[84:85], v[84:85], v[98:99] op_sel_hi:[1,0]
	v_pk_mul_f32 v[88:89], v[82:83], v[98:99] op_sel_hi:[1,0]
	v_pk_mul_f32 v[82:83], v[80:81], v[98:99] op_sel_hi:[1,0]
	v_cvt_pk_bf16_f32 v80, v84, v85
	v_cvt_pk_bf16_f32 v81, v86, v87
	s_nop 0
	v_cvt_pk_bf16_f32 v82, v82, v83
	v_cvt_pk_bf16_f32 v83, v88, v89
	global_store_dwordx4 v[100:101], v[80:83], off offset:256
	s_cbranch_vccnz .LBB0_77
	s_nop 1
	v_fmamk_f32 v80, v223, 0x3a000000, v239
	v_rsq_f32_e32 v96, v80
; __device__ __forceinline__ unsigned cvt_pk_bf16(float lo, float hi) { unsigned r; asm volatile("v_cvt_pk_bf16_f32 %0, %1, %2" : "=v"(r) : "v"(lo), "v"(hi)); return r; }
;     __device__ __forceinline__ void operator()(const f32x4 (&acc)[2][2][4][2], const Unit& u, int wr, int wc, int fr, int fq) const {
;     ...
;             for (int m = 0; m < 4; ++m) { const int row = row0 + ai * HALF + m * 16; bf16_t* rowp = O + (size_t)row * ldc + col0;
;                 const float rs = ssq ? __builtin_amdgcn_rsqf(ssq[row] * (1.f / 2048.f) + 1e-6f) : 1.f;
; #pragma unroll
;                 for (int bj = 0; bj < 2; ++bj) { f32x4 v0 = acc[ai][bj][m][0] * rs, v1 = acc[ai][bj][m][1] * rs;
;                     if (ACT == 1) {
; #pragma unroll
;                         for (int e = 0; e < 4; ++e) { float a = fmaxf(v0[e], 0.f), b = fmaxf(v1[e], 0.f); v0[e] = a * a; v1[e] = b * b; } }
;                     u32x4 w; w.x = cvt_pk_bf16(v0[0], v0[1]); w.y = cvt_pk_bf16(v0[2], v0[3]); w.z = cvt_pk_bf16(v1[0], v1[1]); w.w = cvt_pk_bf16(v1[2], v1[3]);
;                     if (ACT == 1) __builtin_nontemporal_store(w, (u32x4*)(rowp + bj * HALF)); else *(u32x4*)(rowp + bj * HALF) = w; } }
.LBB0_77:
	s_nop 0
	v_add_u32_e32 v82, 48, v138
	v_mov_b64_e32 v[80:81], s[20:21]
	v_mad_i64_i32 v[80:81], s[62:63], v82, s53, v[80:81]
	v_lshl_add_u64 v[80:81], v[142:143], 1, v[80:81]
	v_pk_mul_f32 v[78:79], v[78:79], v[96:97] op_sel_hi:[1,0]
	v_pk_mul_f32 v[76:77], v[76:77], v[96:97] op_sel_hi:[1,0]
	v_pk_mul_f32 v[82:83], v[74:75], v[96:97] op_sel_hi:[1,0]
	v_pk_mul_f32 v[74:75], v[72:73], v[96:97] op_sel_hi:[1,0]
	v_cvt_pk_bf16_f32 v72, v76, v77
	v_cvt_pk_bf16_f32 v73, v78, v79
	v_pk_mul_f32 v[70:71], v[70:71], v[96:97] op_sel_hi:[1,0]
	v_cvt_pk_bf16_f32 v74, v74, v75
	v_cvt_pk_bf16_f32 v75, v82, v83
	global_store_dwordx4 v[80:81], v[72:75], off
	v_pk_mul_f32 v[68:69], v[68:69], v[96:97] op_sel_hi:[1,0]
	s_and_b64 vcc, exec, s[4:5]
	v_pk_mul_f32 v[72:73], v[66:67], v[96:97] op_sel_hi:[1,0]
	v_pk_mul_f32 v[66:67], v[64:65], v[96:97] op_sel_hi:[1,0]
	v_cvt_pk_bf16_f32 v64, v68, v69
	v_cvt_pk_bf16_f32 v65, v70, v71
	s_nop 0
	v_cvt_pk_bf16_f32 v66, v66, v67
	v_cvt_pk_bf16_f32 v67, v72, v73
	global_store_dwordx4 v[80:81], v[64:67], off offset:256
	s_nop 1
	v_mov_b32_e32 v64, 1.0
	v_mov_b32_e32 v66, 1.0
	s_cbranch_vccnz .LBB0_79
	s_nop 1
	v_fmamk_f32 v65, v224, 0x3a000000, v239
	v_rsq_f32_e32 v66, v65
.LBB0_79:
	v_add_u32_e32 v65, 0x80, v138
	v_mov_b64_e32 v[68:69], s[20:21]
	v_mad_i64_i32 v[68:69], s[62:63], v65, s53, v[68:69]
	v_lshl_add_u64 v[68:69], v[142:143], 1, v[68:69]
	v_pk_mul_f32 v[62:63], v[62:63], v[66:67] op_sel_hi:[1,0]
	v_pk_mul_f32 v[60:61], v[60:61], v[66:67] op_sel_hi:[1,0]
	v_pk_mul_f32 v[70:71], v[58:59], v[66:67] op_sel_hi:[1,0]
	v_pk_mul_f32 v[58:59], v[56:57], v[66:67] op_sel_hi:[1,0]
	v_cvt_pk_bf16_f32 v56, v60, v61
	v_cvt_pk_bf16_f32 v57, v62, v63
	s_and_b64 vcc, exec, s[4:5]
	v_cvt_pk_bf16_f32 v58, v58, v59
	v_cvt_pk_bf16_f32 v59, v70, v71
	global_store_dwordx4 v[68:69], v[56:59], off
	v_pk_mul_f32 v[54:55], v[54:55], v[66:67] op_sel_hi:[1,0]
	v_pk_mul_f32 v[52:53], v[52:53], v[66:67] op_sel_hi:[1,0]
	v_pk_mul_f32 v[56:57], v[50:51], v[66:67] op_sel_hi:[1,0]
	v_pk_mul_f32 v[50:51], v[48:49], v[66:67] op_sel_hi:[1,0]
	v_cvt_pk_bf16_f32 v48, v52, v53
	v_cvt_pk_bf16_f32 v49, v54, v55
	s_nop 0
	v_cvt_pk_bf16_f32 v50, v50, v51
	v_cvt_pk_bf16_f32 v51, v56, v57
	global_store_dwordx4 v[68:69], v[48:51], off offset:256
	s_cbranch_vccnz .LBB0_81
	s_nop 1
	v_fmamk_f32 v48, v225, 0x3a000000, v239
	v_rsq_f32_e32 v64, v48
.LBB0_81:
	s_nop 0
	v_add_u32_e32 v50, 0x90, v138
	v_mov_b64_e32 v[48:49], s[20:21]
	v_mad_i64_i32 v[48:49], s[62:63], v50, s53, v[48:49]
	v_lshl_add_u64 v[48:49], v[142:143], 1, v[48:49]
	v_pk_mul_f32 v[46:47], v[46:47], v[64:65] op_sel_hi:[1,0]
	v_pk_mul_f32 v[44:45], v[44:45], v[64:65] op_sel_hi:[1,0]
	v_pk_mul_f32 v[50:51], v[42:43], v[64:65] op_sel_hi:[1,0]
	v_pk_mul_f32 v[42:43], v[40:41], v[64:65] op_sel_hi:[1,0]
	v_cvt_pk_bf16_f32 v40, v44, v45
	v_cvt_pk_bf16_f32 v41, v46, v47
	v_pk_mul_f32 v[38:39], v[38:39], v[64:65] op_sel_hi:[1,0]
	v_cvt_pk_bf16_f32 v42, v42, v43
	v_cvt_pk_bf16_f32 v43, v50, v51
	global_store_dwordx4 v[48:49], v[40:43], off
	v_pk_mul_f32 v[36:37], v[36:37], v[64:65] op_sel_hi:[1,0]
	s_and_b64 vcc, exec, s[4:5]
	v_pk_mul_f32 v[40:41], v[34:35], v[64:65] op_sel_hi:[1,0]
	v_pk_mul_f32 v[34:35], v[32:33], v[64:65] op_sel_hi:[1,0]
	v_cvt_pk_bf16_f32 v32, v36, v37
	v_cvt_pk_bf16_f32 v33, v38, v39
	s_nop 0
	v_cvt_pk_bf16_f32 v34, v34, v35
	v_cvt_pk_bf16_f32 v35, v40, v41
	global_store_dwordx4 v[48:49], v[32:35], off offset:256
	s_nop 1
	v_mov_b32_e32 v32, 1.0
	v_mov_b32_e32 v34, 1.0
	s_cbranch_vccnz .LBB0_83
	s_nop 1
	v_fmamk_f32 v33, v226, 0x3a000000, v239
	v_rsq_f32_e32 v34, v33
.LBB0_83:
	v_add_u32_e32 v33, 0xa0, v138
	v_mov_b64_e32 v[36:37], s[20:21]
	v_mad_i64_i32 v[36:37], s[62:63], v33, s53, v[36:37]
	v_lshl_add_u64 v[36:37], v[142:143], 1, v[36:37]
	v_pk_mul_f32 v[30:31], v[30:31], v[34:35] op_sel_hi:[1,0]
	v_pk_mul_f32 v[28:29], v[28:29], v[34:35] op_sel_hi:[1,0]
	v_pk_mul_f32 v[38:39], v[26:27], v[34:35] op_sel_hi:[1,0]
	v_pk_mul_f32 v[26:27], v[24:25], v[34:35] op_sel_hi:[1,0]
	v_cvt_pk_bf16_f32 v24, v28, v29
	v_cvt_pk_bf16_f32 v25, v30, v31
	s_and_b64 vcc, exec, s[4:5]
	v_cvt_pk_bf16_f32 v26, v26, v27
	v_cvt_pk_bf16_f32 v27, v38, v39
	global_store_dwordx4 v[36:37], v[24:27], off
	v_pk_mul_f32 v[22:23], v[22:23], v[34:35] op_sel_hi:[1,0]
	v_pk_mul_f32 v[20:21], v[20:21], v[34:35] op_sel_hi:[1,0]
	v_pk_mul_f32 v[24:25], v[18:19], v[34:35] op_sel_hi:[1,0]
	v_pk_mul_f32 v[18:19], v[16:17], v[34:35] op_sel_hi:[1,0]
	v_cvt_pk_bf16_f32 v16, v20, v21
	v_cvt_pk_bf16_f32 v17, v22, v23
	s_nop 0
	v_cvt_pk_bf16_f32 v18, v18, v19
	v_cvt_pk_bf16_f32 v19, v24, v25
	global_store_dwordx4 v[36:37], v[16:19], off offset:256
	s_cbranch_vccnz .LBB0_85
	s_nop 1
	v_fmamk_f32 v16, v227, 0x3a000000, v239
	v_rsq_f32_e32 v32, v16
